# SwiGLU epilogue rewritten with packed f32 math (pk_fma/pk_mul/pk_add), all 8 rstd computed up front; same formula and dtypes
# speedup vs baseline: 1.0027x; 1.0027x over previous
; __device__ __forceinline__ unsigned cvt_pk_bf16(float lo, float hi) { unsigned r; asm volatile("v_cvt_pk_bf16_f32 %0, %1, %2" : "=v"(r) : "v"(lo), "v"(hi)); return r; }
; __device__ __forceinline__ float silu_f(float g) { return g * __builtin_amdgcn_rcpf(1.0f + __expf(-g)); }
;     __device__ __forceinline__ void operator()(const f32x4 (&acc)[2][2][4][2], const Unit& u, int wr, int wc, int fr, int fq) const {
;         const int r00 = u.pm * BM;
;         const int b = r00 < 32768 ? (r00 >> 11) : 16 + ((r00 - 32768) >> 12);
;         const int row0 = r00 + wr * 64 + fr; const int col0 = u.pn * 128 + wc * 32 + 8 * fq;
;         const float* sp = shw + (size_t)b * 5632 + u.pn * BM + wc * 32 + 8 * fq;
;         const f32x4 sg0 = *(const f32x4*)(sp), sg1 = *(const f32x4*)(sp + 4), su0 = *(const f32x4*)(sp + HALF), su1 = *(const f32x4*)(sp + HALF + 4);
; #pragma unroll
;         for (int ai = 0; ai < 2; ++ai)
; #pragma unroll
;             for (int m = 0; m < 4; ++m) {
;                 const int row = row0 + ai * HALF + m * 16;
;                 const float rs = __builtin_amdgcn_rsqf(ssq[row] * (1.0f / 1024.0f) + 1e-6f);
;                 bf16_t* rowp = O + (size_t)row * 2816 + col0;
;                 const f32x4 g0 = acc[ai][0][m][0] * rs + sg0, g1 = acc[ai][0][m][1] * rs + sg1, u0 = acc[ai][1][m][0] * rs + su0, u1 = acc[ai][1][m][1] * rs + su1;
;                 u32x4 w;
;                 w.x = cvt_pk_bf16(silu_f(g0[0]) * u0[0], silu_f(g0[1]) * u0[1]);
;                 w.y = cvt_pk_bf16(silu_f(g0[2]) * u0[2], silu_f(g0[3]) * u0[3]);
;                 w.z = cvt_pk_bf16(silu_f(g1[0]) * u1[0], silu_f(g1[1]) * u1[1]);
;                 w.w = cvt_pk_bf16(silu_f(g1[2]) * u1[2], silu_f(g1[3]) * u1[3]);
;                 *(u32x4*)rowp = w;
.LBB0_403:
	s_lshl_b32 s9, s1, 8
	s_add_i32 s17, s9, 0xffff8000
	s_lshr_b32 s17, s17, 12
	s_ashr_i32 s16, s1, 3
	s_add_i32 s17, s17, 16
	s_cmpk_lt_i32 s1, 0x80
	s_cselect_b32 s1, s16, s17
	v_add_u32_e32 v154, s9, v175
	s_mul_hi_i32 s9, s1, 0x5800
	s_mulk_i32 s1, 0x5800
	s_add_u32 s16, s22, s1
	v_lshl_or_b32 v176, s0, 7, v181
	s_addc_u32 s9, s63, s9
	s_lshl_b32 s0, s0, 8
	s_ashr_i32 s1, s0, 31
	s_lshl_b64 s[0:1], s[0:1], 2
	s_add_u32 s0, s16, s0
	s_addc_u32 s1, s9, s1
	s_add_u32 s0, s0, s86
	v_ashrrev_i32_e32 v155, 31, v154
	s_addc_u32 s1, s1, 0
	v_lshl_add_u64 v[156:157], v[154:155], 2, s[28:29]
	global_load_dwordx4 v[52:55], v183, s[0:1] offset:16
	global_load_dwordx4 v[60:63], v183, s[0:1]
	global_load_dwordx4 v[48:51], v183, s[0:1] offset:528
	global_load_dwordx4 v[56:59], v183, s[0:1] offset:512
	global_load_dword v155, v[156:157], off
	global_load_dword v192, v[156:157], off offset:64
	global_load_dword v193, v[156:157], off offset:128
	global_load_dword v194, v[156:157], off offset:192
	global_load_dword v195, v[156:157], off offset:512
	global_load_dword v196, v[156:157], off offset:576
	global_load_dword v197, v[156:157], off offset:640
	global_load_dword v198, v[156:157], off offset:704
	v_ashrrev_i32_e32 v177, 31, v176
	v_mov_b64_e32 v[158:159], s[12:13]
	v_mad_i64_i32 v[178:179], s[0:1], v154, s99, v[158:159]
	v_lshlrev_b64 v[176:177], 1, v[176:177]
	v_lshl_add_u64 v[178:179], v[178:179], 0, v[176:177]
	s_mov_b64 s[40:41], -1
	s_andn2_b64 vcc, exec, s[42:43]
	s_waitcnt vmcnt(0)
	v_mov_b32_e32 v216, 0xbfb8aa3b
	v_fmamk_f32 v200, v155, 0x3a800000, v224
	v_fmamk_f32 v202, v192, 0x3a800000, v224
	v_fmamk_f32 v204, v193, 0x3a800000, v224
	v_fmamk_f32 v206, v194, 0x3a800000, v224
	v_fmamk_f32 v208, v195, 0x3a800000, v224
	v_fmamk_f32 v210, v196, 0x3a800000, v224
	v_fmamk_f32 v212, v197, 0x3a800000, v224
	v_fmamk_f32 v214, v198, 0x3a800000, v224
	v_rsq_f32_e32 v200, v200
	v_rsq_f32_e32 v202, v202
	v_rsq_f32_e32 v204, v204
	v_rsq_f32_e32 v206, v206
	v_rsq_f32_e32 v208, v208
	v_rsq_f32_e32 v210, v210
	v_rsq_f32_e32 v212, v212
	v_rsq_f32_e32 v214, v214
	v_pk_fma_f32 v[140:141], v[140:141], v[200:201], v[60:61] op_sel_hi:[1,0,1]
	v_pk_fma_f32 v[142:143], v[142:143], v[200:201], v[62:63] op_sel_hi:[1,0,1]
	v_pk_fma_f32 v[136:137], v[136:137], v[200:201], v[52:53] op_sel_hi:[1,0,1]
	v_pk_fma_f32 v[138:139], v[138:139], v[200:201], v[54:55] op_sel_hi:[1,0,1]
	v_pk_mul_f32 v[192:193], v[140:141], v[216:217] op_sel_hi:[1,0]
	v_pk_mul_f32 v[194:195], v[142:143], v[216:217] op_sel_hi:[1,0]
	v_pk_mul_f32 v[196:197], v[136:137], v[216:217] op_sel_hi:[1,0]
	v_pk_mul_f32 v[198:199], v[138:139], v[216:217] op_sel_hi:[1,0]
	v_pk_fma_f32 v[132:133], v[132:133], v[200:201], v[56:57] op_sel_hi:[1,0,1]
	v_pk_fma_f32 v[134:135], v[134:135], v[200:201], v[58:59] op_sel_hi:[1,0,1]
	v_pk_fma_f32 v[128:129], v[128:129], v[200:201], v[48:49] op_sel_hi:[1,0,1]
	v_pk_fma_f32 v[130:131], v[130:131], v[200:201], v[50:51] op_sel_hi:[1,0,1]
	v_exp_f32_e32 v192, v192
	v_exp_f32_e32 v193, v193
	v_exp_f32_e32 v194, v194
	v_exp_f32_e32 v195, v195
	v_exp_f32_e32 v196, v196
	v_exp_f32_e32 v197, v197
	v_exp_f32_e32 v198, v198
	v_exp_f32_e32 v199, v199
	v_pk_mul_f32 v[140:141], v[140:141], v[132:133]
	v_pk_mul_f32 v[142:143], v[142:143], v[134:135]
	v_pk_mul_f32 v[136:137], v[136:137], v[128:129]
	v_pk_mul_f32 v[138:139], v[138:139], v[130:131]
	v_pk_add_f32 v[192:193], v[192:193], 1.0 op_sel_hi:[1,0]
	v_pk_add_f32 v[194:195], v[194:195], 1.0 op_sel_hi:[1,0]
	v_pk_add_f32 v[196:197], v[196:197], 1.0 op_sel_hi:[1,0]
	v_pk_add_f32 v[198:199], v[198:199], 1.0 op_sel_hi:[1,0]
	v_rcp_f32_e32 v192, v192
	v_rcp_f32_e32 v193, v193
	v_rcp_f32_e32 v194, v194
	v_rcp_f32_e32 v195, v195
	v_rcp_f32_e32 v196, v196
	v_rcp_f32_e32 v197, v197
	v_rcp_f32_e32 v198, v198
	v_rcp_f32_e32 v199, v199
	v_pk_mul_f32 v[140:141], v[140:141], v[192:193]
	v_pk_mul_f32 v[142:143], v[142:143], v[194:195]
	v_pk_mul_f32 v[136:137], v[136:137], v[196:197]
	v_pk_mul_f32 v[138:139], v[138:139], v[198:199]
	v_cvt_pk_bf16_f32 v188, v140, v141
	v_cvt_pk_bf16_f32 v189, v142, v143
	v_cvt_pk_bf16_f32 v190, v136, v137
	v_cvt_pk_bf16_f32 v191, v138, v139
	global_store_dwordx4 v[178:179], v[188:191], off
	v_or_b32_e32 v186, 16, v154
	v_mad_i64_i32 v[186:187], s[0:1], v186, s99, v[158:159]
	v_lshl_add_u64 v[186:187], v[186:187], 0, v[176:177]
	v_pk_fma_f32 v[124:125], v[124:125], v[202:203], v[60:61] op_sel_hi:[1,0,1]
	v_pk_fma_f32 v[126:127], v[126:127], v[202:203], v[62:63] op_sel_hi:[1,0,1]
	v_pk_fma_f32 v[120:121], v[120:121], v[202:203], v[52:53] op_sel_hi:[1,0,1]
	v_pk_fma_f32 v[122:123], v[122:123], v[202:203], v[54:55] op_sel_hi:[1,0,1]
	v_pk_mul_f32 v[192:193], v[124:125], v[216:217] op_sel_hi:[1,0]
	v_pk_mul_f32 v[194:195], v[126:127], v[216:217] op_sel_hi:[1,0]
	v_pk_mul_f32 v[196:197], v[120:121], v[216:217] op_sel_hi:[1,0]
	v_pk_mul_f32 v[198:199], v[122:123], v[216:217] op_sel_hi:[1,0]
	v_pk_fma_f32 v[116:117], v[116:117], v[202:203], v[56:57] op_sel_hi:[1,0,1]
	v_pk_fma_f32 v[118:119], v[118:119], v[202:203], v[58:59] op_sel_hi:[1,0,1]
	v_pk_fma_f32 v[112:113], v[112:113], v[202:203], v[48:49] op_sel_hi:[1,0,1]
	v_pk_fma_f32 v[114:115], v[114:115], v[202:203], v[50:51] op_sel_hi:[1,0,1]
	v_exp_f32_e32 v192, v192
	v_exp_f32_e32 v193, v193
	v_exp_f32_e32 v194, v194
	v_exp_f32_e32 v195, v195
	v_exp_f32_e32 v196, v196
	v_exp_f32_e32 v197, v197
	v_exp_f32_e32 v198, v198
	v_exp_f32_e32 v199, v199
	v_pk_mul_f32 v[124:125], v[124:125], v[116:117]
	v_pk_mul_f32 v[126:127], v[126:127], v[118:119]
	v_pk_mul_f32 v[120:121], v[120:121], v[112:113]
	v_pk_mul_f32 v[122:123], v[122:123], v[114:115]
; __device__ __forceinline__ unsigned cvt_pk_bf16(float lo, float hi) { unsigned r; asm volatile("v_cvt_pk_bf16_f32 %0, %1, %2" : "=v"(r) : "v"(lo), "v"(hi)); return r; }
; __device__ __forceinline__ float silu_f(float g) { return g * __builtin_amdgcn_rcpf(1.0f + __expf(-g)); }
;     __device__ __forceinline__ void operator()(const f32x4 (&acc)[2][2][4][2], const Unit& u, int wr, int wc, int fr, int fq) const {
;     ...
;             for (int m = 0; m < 4; ++m) {
;                 const int row = row0 + ai * HALF + m * 16;
;                 const float rs = __builtin_amdgcn_rsqf(ssq[row] * (1.0f / 1024.0f) + 1e-6f);
;                 bf16_t* rowp = O + (size_t)row * 2816 + col0;
;                 const f32x4 g0 = acc[ai][0][m][0] * rs + sg0, g1 = acc[ai][0][m][1] * rs + sg1, u0 = acc[ai][1][m][0] * rs + su0, u1 = acc[ai][1][m][1] * rs + su1;
;                 u32x4 w;
;                 w.x = cvt_pk_bf16(silu_f(g0[0]) * u0[0], silu_f(g0[1]) * u0[1]);
;                 w.y = cvt_pk_bf16(silu_f(g0[2]) * u0[2], silu_f(g0[3]) * u0[3]);
;                 w.z = cvt_pk_bf16(silu_f(g1[0]) * u1[0], silu_f(g1[1]) * u1[1]);
;                 w.w = cvt_pk_bf16(silu_f(g1[2]) * u1[2], silu_f(g1[3]) * u1[3]);
;                 *(u32x4*)rowp = w;
	v_pk_add_f32 v[192:193], v[192:193], 1.0 op_sel_hi:[1,0]
	v_pk_add_f32 v[194:195], v[194:195], 1.0 op_sel_hi:[1,0]
	v_pk_add_f32 v[196:197], v[196:197], 1.0 op_sel_hi:[1,0]
	v_pk_add_f32 v[198:199], v[198:199], 1.0 op_sel_hi:[1,0]
	v_rcp_f32_e32 v192, v192
	v_rcp_f32_e32 v193, v193
	v_rcp_f32_e32 v194, v194
	v_rcp_f32_e32 v195, v195
	v_rcp_f32_e32 v196, v196
	v_rcp_f32_e32 v197, v197
	v_rcp_f32_e32 v198, v198
	v_rcp_f32_e32 v199, v199
	v_pk_mul_f32 v[124:125], v[124:125], v[192:193]
	v_pk_mul_f32 v[126:127], v[126:127], v[194:195]
	v_pk_mul_f32 v[120:121], v[120:121], v[196:197]
	v_pk_mul_f32 v[122:123], v[122:123], v[198:199]
	v_cvt_pk_bf16_f32 v218, v124, v125
	v_cvt_pk_bf16_f32 v219, v126, v127
	v_cvt_pk_bf16_f32 v220, v120, v121
	v_cvt_pk_bf16_f32 v221, v122, v123
	global_store_dwordx4 v[186:187], v[218:221], off
	v_or_b32_e32 v186, 32, v154
	v_mad_i64_i32 v[186:187], s[0:1], v186, s99, v[158:159]
	v_lshl_add_u64 v[186:187], v[186:187], 0, v[176:177]
	v_pk_fma_f32 v[108:109], v[108:109], v[204:205], v[60:61] op_sel_hi:[1,0,1]
	v_pk_fma_f32 v[110:111], v[110:111], v[204:205], v[62:63] op_sel_hi:[1,0,1]
	v_pk_fma_f32 v[104:105], v[104:105], v[204:205], v[52:53] op_sel_hi:[1,0,1]
	v_pk_fma_f32 v[106:107], v[106:107], v[204:205], v[54:55] op_sel_hi:[1,0,1]
	v_pk_mul_f32 v[192:193], v[108:109], v[216:217] op_sel_hi:[1,0]
	v_pk_mul_f32 v[194:195], v[110:111], v[216:217] op_sel_hi:[1,0]
	v_pk_mul_f32 v[196:197], v[104:105], v[216:217] op_sel_hi:[1,0]
	v_pk_mul_f32 v[198:199], v[106:107], v[216:217] op_sel_hi:[1,0]
	v_pk_fma_f32 v[100:101], v[100:101], v[204:205], v[56:57] op_sel_hi:[1,0,1]
	v_pk_fma_f32 v[102:103], v[102:103], v[204:205], v[58:59] op_sel_hi:[1,0,1]
	v_pk_fma_f32 v[96:97], v[96:97], v[204:205], v[48:49] op_sel_hi:[1,0,1]
	v_pk_fma_f32 v[98:99], v[98:99], v[204:205], v[50:51] op_sel_hi:[1,0,1]
	v_exp_f32_e32 v192, v192
	v_exp_f32_e32 v193, v193
	v_exp_f32_e32 v194, v194
	v_exp_f32_e32 v195, v195
	v_exp_f32_e32 v196, v196
	v_exp_f32_e32 v197, v197
	v_exp_f32_e32 v198, v198
	v_exp_f32_e32 v199, v199
	v_pk_mul_f32 v[108:109], v[108:109], v[100:101]
	v_pk_mul_f32 v[110:111], v[110:111], v[102:103]
	v_pk_mul_f32 v[104:105], v[104:105], v[96:97]
	v_pk_mul_f32 v[106:107], v[106:107], v[98:99]
	v_pk_add_f32 v[192:193], v[192:193], 1.0 op_sel_hi:[1,0]
	v_pk_add_f32 v[194:195], v[194:195], 1.0 op_sel_hi:[1,0]
	v_pk_add_f32 v[196:197], v[196:197], 1.0 op_sel_hi:[1,0]
	v_pk_add_f32 v[198:199], v[198:199], 1.0 op_sel_hi:[1,0]
	v_rcp_f32_e32 v192, v192
	v_rcp_f32_e32 v193, v193
	v_rcp_f32_e32 v194, v194
	v_rcp_f32_e32 v195, v195
	v_rcp_f32_e32 v196, v196
	v_rcp_f32_e32 v197, v197
	v_rcp_f32_e32 v198, v198
	v_rcp_f32_e32 v199, v199
	v_pk_mul_f32 v[108:109], v[108:109], v[192:193]
	v_pk_mul_f32 v[110:111], v[110:111], v[194:195]
	v_pk_mul_f32 v[104:105], v[104:105], v[196:197]
	v_pk_mul_f32 v[106:107], v[106:107], v[198:199]
	v_cvt_pk_bf16_f32 v188, v108, v109
	v_cvt_pk_bf16_f32 v189, v110, v111
	v_cvt_pk_bf16_f32 v190, v104, v105
	v_cvt_pk_bf16_f32 v191, v106, v107
	global_store_dwordx4 v[186:187], v[188:191], off
	v_or_b32_e32 v186, 48, v154
	v_mad_i64_i32 v[186:187], s[0:1], v186, s99, v[158:159]
	v_lshl_add_u64 v[186:187], v[186:187], 0, v[176:177]
	v_pk_fma_f32 v[92:93], v[92:93], v[206:207], v[60:61] op_sel_hi:[1,0,1]
	v_pk_fma_f32 v[94:95], v[94:95], v[206:207], v[62:63] op_sel_hi:[1,0,1]
	v_pk_fma_f32 v[88:89], v[88:89], v[206:207], v[52:53] op_sel_hi:[1,0,1]
	v_pk_fma_f32 v[90:91], v[90:91], v[206:207], v[54:55] op_sel_hi:[1,0,1]
	v_pk_mul_f32 v[192:193], v[92:93], v[216:217] op_sel_hi:[1,0]
	v_pk_mul_f32 v[194:195], v[94:95], v[216:217] op_sel_hi:[1,0]
	v_pk_mul_f32 v[196:197], v[88:89], v[216:217] op_sel_hi:[1,0]
	v_pk_mul_f32 v[198:199], v[90:91], v[216:217] op_sel_hi:[1,0]
	v_pk_fma_f32 v[84:85], v[84:85], v[206:207], v[56:57] op_sel_hi:[1,0,1]
	v_pk_fma_f32 v[86:87], v[86:87], v[206:207], v[58:59] op_sel_hi:[1,0,1]
	v_pk_fma_f32 v[80:81], v[80:81], v[206:207], v[48:49] op_sel_hi:[1,0,1]
	v_pk_fma_f32 v[82:83], v[82:83], v[206:207], v[50:51] op_sel_hi:[1,0,1]
	v_exp_f32_e32 v192, v192
	v_exp_f32_e32 v193, v193
	v_exp_f32_e32 v194, v194
	v_exp_f32_e32 v195, v195
	v_exp_f32_e32 v196, v196
	v_exp_f32_e32 v197, v197
	v_exp_f32_e32 v198, v198
	v_exp_f32_e32 v199, v199
	v_pk_mul_f32 v[92:93], v[92:93], v[84:85]
	v_pk_mul_f32 v[94:95], v[94:95], v[86:87]
	v_pk_mul_f32 v[88:89], v[88:89], v[80:81]
	v_pk_mul_f32 v[90:91], v[90:91], v[82:83]
	v_pk_add_f32 v[192:193], v[192:193], 1.0 op_sel_hi:[1,0]
	v_pk_add_f32 v[194:195], v[194:195], 1.0 op_sel_hi:[1,0]
	v_pk_add_f32 v[196:197], v[196:197], 1.0 op_sel_hi:[1,0]
	v_pk_add_f32 v[198:199], v[198:199], 1.0 op_sel_hi:[1,0]
	v_rcp_f32_e32 v192, v192
	v_rcp_f32_e32 v193, v193
	v_rcp_f32_e32 v194, v194
	v_rcp_f32_e32 v195, v195
	v_rcp_f32_e32 v196, v196
	v_rcp_f32_e32 v197, v197
	v_rcp_f32_e32 v198, v198
	v_rcp_f32_e32 v199, v199
	v_pk_mul_f32 v[92:93], v[92:93], v[192:193]
	v_pk_mul_f32 v[94:95], v[94:95], v[194:195]
	v_pk_mul_f32 v[88:89], v[88:89], v[196:197]
	v_pk_mul_f32 v[90:91], v[90:91], v[198:199]
	v_cvt_pk_bf16_f32 v218, v92, v93
	v_cvt_pk_bf16_f32 v219, v94, v95
	v_cvt_pk_bf16_f32 v220, v88, v89
	v_cvt_pk_bf16_f32 v221, v90, v91
	global_store_dwordx4 v[186:187], v[218:221], off
	v_add_u32_e32 v186, 0x80, v154
	v_mad_i64_i32 v[186:187], s[0:1], v186, s99, v[158:159]
	v_lshl_add_u64 v[186:187], v[186:187], 0, v[176:177]
	v_pk_fma_f32 v[76:77], v[76:77], v[208:209], v[60:61] op_sel_hi:[1,0,1]
	v_pk_fma_f32 v[78:79], v[78:79], v[208:209], v[62:63] op_sel_hi:[1,0,1]
	v_pk_fma_f32 v[72:73], v[72:73], v[208:209], v[52:53] op_sel_hi:[1,0,1]
	v_pk_fma_f32 v[74:75], v[74:75], v[208:209], v[54:55] op_sel_hi:[1,0,1]
; __device__ __forceinline__ unsigned cvt_pk_bf16(float lo, float hi) { unsigned r; asm volatile("v_cvt_pk_bf16_f32 %0, %1, %2" : "=v"(r) : "v"(lo), "v"(hi)); return r; }
; __device__ __forceinline__ float silu_f(float g) { return g * __builtin_amdgcn_rcpf(1.0f + __expf(-g)); }
;     __device__ __forceinline__ void operator()(const f32x4 (&acc)[2][2][4][2], const Unit& u, int wr, int wc, int fr, int fq) const {
;     ...
;             for (int m = 0; m < 4; ++m) {
;                 const int row = row0 + ai * HALF + m * 16;
;                 const float rs = __builtin_amdgcn_rsqf(ssq[row] * (1.0f / 1024.0f) + 1e-6f);
;                 bf16_t* rowp = O + (size_t)row * 2816 + col0;
;                 const f32x4 g0 = acc[ai][0][m][0] * rs + sg0, g1 = acc[ai][0][m][1] * rs + sg1, u0 = acc[ai][1][m][0] * rs + su0, u1 = acc[ai][1][m][1] * rs + su1;
;                 u32x4 w;
;                 w.x = cvt_pk_bf16(silu_f(g0[0]) * u0[0], silu_f(g0[1]) * u0[1]);
;                 w.y = cvt_pk_bf16(silu_f(g0[2]) * u0[2], silu_f(g0[3]) * u0[3]);
;                 w.z = cvt_pk_bf16(silu_f(g1[0]) * u1[0], silu_f(g1[1]) * u1[1]);
;                 w.w = cvt_pk_bf16(silu_f(g1[2]) * u1[2], silu_f(g1[3]) * u1[3]);
;                 *(u32x4*)rowp = w;
	v_pk_mul_f32 v[192:193], v[76:77], v[216:217] op_sel_hi:[1,0]
	v_pk_mul_f32 v[194:195], v[78:79], v[216:217] op_sel_hi:[1,0]
	v_pk_mul_f32 v[196:197], v[72:73], v[216:217] op_sel_hi:[1,0]
	v_pk_mul_f32 v[198:199], v[74:75], v[216:217] op_sel_hi:[1,0]
	v_pk_fma_f32 v[68:69], v[68:69], v[208:209], v[56:57] op_sel_hi:[1,0,1]
	v_pk_fma_f32 v[70:71], v[70:71], v[208:209], v[58:59] op_sel_hi:[1,0,1]
	v_pk_fma_f32 v[64:65], v[64:65], v[208:209], v[48:49] op_sel_hi:[1,0,1]
	v_pk_fma_f32 v[66:67], v[66:67], v[208:209], v[50:51] op_sel_hi:[1,0,1]
	v_exp_f32_e32 v192, v192
	v_exp_f32_e32 v193, v193
	v_exp_f32_e32 v194, v194
	v_exp_f32_e32 v195, v195
	v_exp_f32_e32 v196, v196
	v_exp_f32_e32 v197, v197
	v_exp_f32_e32 v198, v198
	v_exp_f32_e32 v199, v199
	v_pk_mul_f32 v[76:77], v[76:77], v[68:69]
	v_pk_mul_f32 v[78:79], v[78:79], v[70:71]
	v_pk_mul_f32 v[72:73], v[72:73], v[64:65]
	v_pk_mul_f32 v[74:75], v[74:75], v[66:67]
	v_pk_add_f32 v[192:193], v[192:193], 1.0 op_sel_hi:[1,0]
	v_pk_add_f32 v[194:195], v[194:195], 1.0 op_sel_hi:[1,0]
	v_pk_add_f32 v[196:197], v[196:197], 1.0 op_sel_hi:[1,0]
	v_pk_add_f32 v[198:199], v[198:199], 1.0 op_sel_hi:[1,0]
	v_rcp_f32_e32 v192, v192
	v_rcp_f32_e32 v193, v193
	v_rcp_f32_e32 v194, v194
	v_rcp_f32_e32 v195, v195
	v_rcp_f32_e32 v196, v196
	v_rcp_f32_e32 v197, v197
	v_rcp_f32_e32 v198, v198
	v_rcp_f32_e32 v199, v199
	v_pk_mul_f32 v[76:77], v[76:77], v[192:193]
	v_pk_mul_f32 v[78:79], v[78:79], v[194:195]
	v_pk_mul_f32 v[72:73], v[72:73], v[196:197]
	v_pk_mul_f32 v[74:75], v[74:75], v[198:199]
	v_cvt_pk_bf16_f32 v188, v76, v77
	v_cvt_pk_bf16_f32 v189, v78, v79
	v_cvt_pk_bf16_f32 v190, v72, v73
	v_cvt_pk_bf16_f32 v191, v74, v75
	global_store_dwordx4 v[186:187], v[188:191], off
	v_add_u32_e32 v186, 0x90, v154
	v_mad_i64_i32 v[186:187], s[0:1], v186, s99, v[158:159]
	v_lshl_add_u64 v[186:187], v[186:187], 0, v[176:177]
	v_pk_fma_f32 v[44:45], v[44:45], v[210:211], v[60:61] op_sel_hi:[1,0,1]
	v_pk_fma_f32 v[46:47], v[46:47], v[210:211], v[62:63] op_sel_hi:[1,0,1]
	v_pk_fma_f32 v[40:41], v[40:41], v[210:211], v[52:53] op_sel_hi:[1,0,1]
	v_pk_fma_f32 v[42:43], v[42:43], v[210:211], v[54:55] op_sel_hi:[1,0,1]
	v_pk_mul_f32 v[192:193], v[44:45], v[216:217] op_sel_hi:[1,0]
	v_pk_mul_f32 v[194:195], v[46:47], v[216:217] op_sel_hi:[1,0]
	v_pk_mul_f32 v[196:197], v[40:41], v[216:217] op_sel_hi:[1,0]
	v_pk_mul_f32 v[198:199], v[42:43], v[216:217] op_sel_hi:[1,0]
	v_pk_fma_f32 v[36:37], v[36:37], v[210:211], v[56:57] op_sel_hi:[1,0,1]
	v_pk_fma_f32 v[38:39], v[38:39], v[210:211], v[58:59] op_sel_hi:[1,0,1]
	v_pk_fma_f32 v[32:33], v[32:33], v[210:211], v[48:49] op_sel_hi:[1,0,1]
	v_pk_fma_f32 v[34:35], v[34:35], v[210:211], v[50:51] op_sel_hi:[1,0,1]
	v_exp_f32_e32 v192, v192
	v_exp_f32_e32 v193, v193
	v_exp_f32_e32 v194, v194
	v_exp_f32_e32 v195, v195
	v_exp_f32_e32 v196, v196
	v_exp_f32_e32 v197, v197
	v_exp_f32_e32 v198, v198
	v_exp_f32_e32 v199, v199
	v_pk_mul_f32 v[44:45], v[44:45], v[36:37]
	v_pk_mul_f32 v[46:47], v[46:47], v[38:39]
	v_pk_mul_f32 v[40:41], v[40:41], v[32:33]
	v_pk_mul_f32 v[42:43], v[42:43], v[34:35]
	v_pk_add_f32 v[192:193], v[192:193], 1.0 op_sel_hi:[1,0]
	v_pk_add_f32 v[194:195], v[194:195], 1.0 op_sel_hi:[1,0]
	v_pk_add_f32 v[196:197], v[196:197], 1.0 op_sel_hi:[1,0]
	v_pk_add_f32 v[198:199], v[198:199], 1.0 op_sel_hi:[1,0]
	v_rcp_f32_e32 v192, v192
	v_rcp_f32_e32 v193, v193
	v_rcp_f32_e32 v194, v194
	v_rcp_f32_e32 v195, v195
	v_rcp_f32_e32 v196, v196
	v_rcp_f32_e32 v197, v197
	v_rcp_f32_e32 v198, v198
	v_rcp_f32_e32 v199, v199
	v_pk_mul_f32 v[44:45], v[44:45], v[192:193]
	v_pk_mul_f32 v[46:47], v[46:47], v[194:195]
	v_pk_mul_f32 v[40:41], v[40:41], v[196:197]
	v_pk_mul_f32 v[42:43], v[42:43], v[198:199]
	v_cvt_pk_bf16_f32 v218, v44, v45
	v_cvt_pk_bf16_f32 v219, v46, v47
	v_cvt_pk_bf16_f32 v220, v40, v41
	v_cvt_pk_bf16_f32 v221, v42, v43
	global_store_dwordx4 v[186:187], v[218:221], off
	v_add_u32_e32 v186, 0xa0, v154
	v_mad_i64_i32 v[186:187], s[0:1], v186, s99, v[158:159]
	v_lshl_add_u64 v[186:187], v[186:187], 0, v[176:177]
	v_pk_fma_f32 v[28:29], v[28:29], v[212:213], v[60:61] op_sel_hi:[1,0,1]
	v_pk_fma_f32 v[30:31], v[30:31], v[212:213], v[62:63] op_sel_hi:[1,0,1]
; __device__ __forceinline__ unsigned cvt_pk_bf16(float lo, float hi) { unsigned r; asm volatile("v_cvt_pk_bf16_f32 %0, %1, %2" : "=v"(r) : "v"(lo), "v"(hi)); return r; }
; #define PG8_BAR __builtin_amdgcn_s_barrier()
; __device__ __forceinline__ float silu_f(float g) { return g * __builtin_amdgcn_rcpf(1.0f + __expf(-g)); }
; template <class Epi, class Sched, bool ALIGN_EPI = false, bool SP2 = false>
; __device__ __forceinline__ void gemm_phase(PG8_LAS unsigned char* lds, const Gemm g, const Sched& S, const Epi& E, const int tid_in) {
;     ...
;         if (!has_next) break;
; #pragma unroll
;         for (int a = 0; a < 2; ++a)
; #pragma unroll
;             for (int b = 0; b < 2; ++b)
; #pragma unroll
;                 for (int m = 0; m < 4; ++m)
; #pragma unroll
;                     for (int n = 0; n < 2; ++n) acc[a][b][m][n] = (f32x4){0.f, 0.f, 0.f, 0.f};
;         cur = nxt; cA = nA; cB = nB; ++ui;
;         if constexpr (ALIGN_EPI) { if (wr == 1) PG8_BAR; }
;     __device__ __forceinline__ void operator()(const f32x4 (&acc)[2][2][4][2], const Unit& u, int wr, int wc, int fr, int fq) const {
;     ...
;             for (int m = 0; m < 4; ++m) {
;                 const int row = row0 + ai * HALF + m * 16;
;                 const float rs = __builtin_amdgcn_rsqf(ssq[row] * (1.0f / 1024.0f) + 1e-6f);
;                 bf16_t* rowp = O + (size_t)row * 2816 + col0;
;                 const f32x4 g0 = acc[ai][0][m][0] * rs + sg0, g1 = acc[ai][0][m][1] * rs + sg1, u0 = acc[ai][1][m][0] * rs + su0, u1 = acc[ai][1][m][1] * rs + su1;
;                 u32x4 w;
;                 w.x = cvt_pk_bf16(silu_f(g0[0]) * u0[0], silu_f(g0[1]) * u0[1]);
;                 w.y = cvt_pk_bf16(silu_f(g0[2]) * u0[2], silu_f(g0[3]) * u0[3]);
;                 w.z = cvt_pk_bf16(silu_f(g1[0]) * u1[0], silu_f(g1[1]) * u1[1]);
;                 w.w = cvt_pk_bf16(silu_f(g1[2]) * u1[2], silu_f(g1[3]) * u1[3]);
;                 *(u32x4*)rowp = w;
	v_pk_fma_f32 v[24:25], v[24:25], v[212:213], v[52:53] op_sel_hi:[1,0,1]
	v_pk_fma_f32 v[26:27], v[26:27], v[212:213], v[54:55] op_sel_hi:[1,0,1]
	v_pk_mul_f32 v[192:193], v[28:29], v[216:217] op_sel_hi:[1,0]
	v_pk_mul_f32 v[194:195], v[30:31], v[216:217] op_sel_hi:[1,0]
	v_pk_mul_f32 v[196:197], v[24:25], v[216:217] op_sel_hi:[1,0]
	v_pk_mul_f32 v[198:199], v[26:27], v[216:217] op_sel_hi:[1,0]
	v_pk_fma_f32 v[20:21], v[20:21], v[212:213], v[56:57] op_sel_hi:[1,0,1]
	v_pk_fma_f32 v[22:23], v[22:23], v[212:213], v[58:59] op_sel_hi:[1,0,1]
	v_pk_fma_f32 v[16:17], v[16:17], v[212:213], v[48:49] op_sel_hi:[1,0,1]
	v_pk_fma_f32 v[18:19], v[18:19], v[212:213], v[50:51] op_sel_hi:[1,0,1]
	v_exp_f32_e32 v192, v192
	v_exp_f32_e32 v193, v193
	v_exp_f32_e32 v194, v194
	v_exp_f32_e32 v195, v195
	v_exp_f32_e32 v196, v196
	v_exp_f32_e32 v197, v197
	v_exp_f32_e32 v198, v198
	v_exp_f32_e32 v199, v199
	v_pk_mul_f32 v[28:29], v[28:29], v[20:21]
	v_pk_mul_f32 v[30:31], v[30:31], v[22:23]
	v_pk_mul_f32 v[24:25], v[24:25], v[16:17]
	v_pk_mul_f32 v[26:27], v[26:27], v[18:19]
	v_pk_add_f32 v[192:193], v[192:193], 1.0 op_sel_hi:[1,0]
	v_pk_add_f32 v[194:195], v[194:195], 1.0 op_sel_hi:[1,0]
	v_pk_add_f32 v[196:197], v[196:197], 1.0 op_sel_hi:[1,0]
	v_pk_add_f32 v[198:199], v[198:199], 1.0 op_sel_hi:[1,0]
	v_rcp_f32_e32 v192, v192
	v_rcp_f32_e32 v193, v193
	v_rcp_f32_e32 v194, v194
	v_rcp_f32_e32 v195, v195
	v_rcp_f32_e32 v196, v196
	v_rcp_f32_e32 v197, v197
	v_rcp_f32_e32 v198, v198
	v_rcp_f32_e32 v199, v199
	v_pk_mul_f32 v[28:29], v[28:29], v[192:193]
	v_pk_mul_f32 v[30:31], v[30:31], v[194:195]
	v_pk_mul_f32 v[24:25], v[24:25], v[196:197]
	v_pk_mul_f32 v[26:27], v[26:27], v[198:199]
	v_cvt_pk_bf16_f32 v188, v28, v29
	v_cvt_pk_bf16_f32 v189, v30, v31
	v_cvt_pk_bf16_f32 v190, v24, v25
	v_cvt_pk_bf16_f32 v191, v26, v27
	global_store_dwordx4 v[186:187], v[188:191], off
	v_add_u32_e32 v186, 0xb0, v154
	v_mad_i64_i32 v[186:187], s[0:1], v186, s99, v[158:159]
	v_lshl_add_u64 v[186:187], v[186:187], 0, v[176:177]
	v_pk_fma_f32 v[12:13], v[12:13], v[214:215], v[60:61] op_sel_hi:[1,0,1]
	v_pk_fma_f32 v[14:15], v[14:15], v[214:215], v[62:63] op_sel_hi:[1,0,1]
	v_pk_fma_f32 v[8:9], v[8:9], v[214:215], v[52:53] op_sel_hi:[1,0,1]
	v_pk_fma_f32 v[10:11], v[10:11], v[214:215], v[54:55] op_sel_hi:[1,0,1]
	v_pk_mul_f32 v[192:193], v[12:13], v[216:217] op_sel_hi:[1,0]
	v_pk_mul_f32 v[194:195], v[14:15], v[216:217] op_sel_hi:[1,0]
	v_pk_mul_f32 v[196:197], v[8:9], v[216:217] op_sel_hi:[1,0]
	v_pk_mul_f32 v[198:199], v[10:11], v[216:217] op_sel_hi:[1,0]
	v_pk_fma_f32 v[4:5], v[4:5], v[214:215], v[56:57] op_sel_hi:[1,0,1]
	v_pk_fma_f32 v[6:7], v[6:7], v[214:215], v[58:59] op_sel_hi:[1,0,1]
	v_pk_fma_f32 v[0:1], v[0:1], v[214:215], v[48:49] op_sel_hi:[1,0,1]
	v_pk_fma_f32 v[2:3], v[2:3], v[214:215], v[50:51] op_sel_hi:[1,0,1]
	v_exp_f32_e32 v192, v192
	v_exp_f32_e32 v193, v193
	v_exp_f32_e32 v194, v194
	v_exp_f32_e32 v195, v195
	v_exp_f32_e32 v196, v196
	v_exp_f32_e32 v197, v197
	v_exp_f32_e32 v198, v198
	v_exp_f32_e32 v199, v199
	v_pk_mul_f32 v[12:13], v[12:13], v[4:5]
	v_pk_mul_f32 v[14:15], v[14:15], v[6:7]
	v_pk_mul_f32 v[8:9], v[8:9], v[0:1]
	v_pk_mul_f32 v[10:11], v[10:11], v[2:3]
	v_pk_add_f32 v[192:193], v[192:193], 1.0 op_sel_hi:[1,0]
	v_pk_add_f32 v[194:195], v[194:195], 1.0 op_sel_hi:[1,0]
	v_pk_add_f32 v[196:197], v[196:197], 1.0 op_sel_hi:[1,0]
	v_pk_add_f32 v[198:199], v[198:199], 1.0 op_sel_hi:[1,0]
	v_rcp_f32_e32 v192, v192
	v_rcp_f32_e32 v193, v193
	v_rcp_f32_e32 v194, v194
	v_rcp_f32_e32 v195, v195
	v_rcp_f32_e32 v196, v196
	v_rcp_f32_e32 v197, v197
	v_rcp_f32_e32 v198, v198
	v_rcp_f32_e32 v199, v199
	v_pk_mul_f32 v[12:13], v[12:13], v[192:193]
	v_pk_mul_f32 v[14:15], v[14:15], v[194:195]
	v_pk_mul_f32 v[8:9], v[8:9], v[196:197]
	v_pk_mul_f32 v[10:11], v[10:11], v[198:199]
	v_cvt_pk_bf16_f32 v218, v12, v13
	v_cvt_pk_bf16_f32 v219, v14, v15
	v_cvt_pk_bf16_f32 v220, v8, v9
	v_cvt_pk_bf16_f32 v221, v10, v11
	global_store_dwordx4 v[186:187], v[218:221], off
	s_cbranch_vccnz .LBB0_396
	s_andn2_b64 vcc, exec, s[34:35]
	s_cbranch_vccnz .LBB0_395
	s_barrier
	s_branch .LBB0_395
